# grid barrier: waiting workgroups poll the arrival counter less often (s_sleep 4 between polls)
# speedup vs baseline: 1.0035x; 1.0035x over previous
.LBB0_878:
	s_and_b32 s20, s18, 0xff
	s_mov_b64 s[16:17], -1
	s_cmp_lg_u32 s20, 0
	s_mov_b64 s[22:23], -1
	s_sleep 4
	s_cbranch_scc0 .LBB0_881
	s_and_b64 vcc, exec, s[22:23]
	s_cbranch_vccz .LBB0_877
